# latent attention K/V loop rewritten with v_mfma_f32_32x32x16_bf16 (same bf16 operands, f32 softmax/accumulate), all 34 tiles in the loop, LDS hand-over to the 16x16 epilogue layout; K/V^T LDS stride b
# speedup vs baseline: 1.0187x; 1.0187x over previous
.LBB0_747:
	s_and_b64 vcc, exec, s[10:11]
	s_cbranch_vccz .LBB0_751
	v_mov_b32_e32 v10, v232
	s_load_dwordx8 s[52:59], s[44:45], 0x60
	v_and_b32_e32 v181, 63, v10
	v_readlane_b32 s10, v255, 20
	v_mov_b32_e32 v3, v0
	s_load_dwordx2 s[42:43], s[44:45], 0xb0
	v_or_b32_e32 v2, s10, v181
	v_lshlrev_b64 v[2:3], 2, v[2:3]
	s_waitcnt lgkmcnt(0)
	v_lshl_add_u64 v[4:5], s[52:53], 0, v[2:3]
	global_load_dword v11, v[4:5], off
	v_lshl_add_u64 v[4:5], s[54:55], 0, v[2:3]
	global_load_dword v12, v[4:5], off
	v_lshl_add_u64 v[4:5], s[56:57], 0, v[2:3]
	v_lshl_add_u64 v[2:3], s[58:59], 0, v[2:3]
	global_load_dword v13, v[4:5], off
	global_load_dword v14, v[2:3], off
	s_add_i32 s6, s37, s48
	s_lshl_b32 s14, s36, 7
	s_lshl_b32 s30, s36, 8
	v_readlane_b32 s11, v255, 21
	s_add_u32 s10, s42, s47
	s_addc_u32 s11, s43, s46
	s_add_u32 s36, s10, s30
	s_addc_u32 s37, s11, 0
	s_lshl_b32 s10, s27, 10
	s_or_b32 s10, s14, s10
	s_mul_hi_i32 s11, s10, 0x2200
	s_mulk_i32 s10, 0x2200
	v_ashrrev_i32_e32 v50, 4, v10
	s_add_u32 s10, s42, s10
	v_ashrrev_i32_e32 v51, 31, v50
	v_and_b32_e32 v177, 15, v10
	s_addc_u32 s11, s43, s11
	v_lshlrev_b64 v[52:53], 11, v[50:51]
	s_add_u32 s40, s10, 0xe010000
	v_lshl_add_u64 v[2:3], s[36:37], 0, v[52:53]
	v_lshlrev_b32_e32 v124, 4, v177
	v_mov_b32_e32 v125, v0
	s_addc_u32 s41, s11, 0
	v_lshl_add_u64 v[2:3], v[2:3], 0, v[124:125]
	s_mov_b32 s15, 0x16810000
	v_mov_b64_e32 v[4:5], s[40:41]
	s_movk_i32 s35, 0x2200
	v_add_co_u32_e32 v6, vcc, s15, v2
	v_mad_i64_i32 v[4:5], s[36:37], v50, s35, v[4:5]
	s_nop 0
	v_addc_co_u32_e32 v7, vcc, 0, v3, vcc
	s_mov_b32 s15, 0x16820000
	v_lshl_add_u64 v[4:5], v[4:5], 0, v[124:125]
	global_load_dwordx4 v[18:21], v[6:7], off
	global_load_dwordx4 v[22:25], v[4:5], off
	v_add_co_u32_e32 v6, vcc, s15, v2
	s_mov_b32 s15, 0x44000
	s_nop 0
	v_addc_co_u32_e32 v7, vcc, 0, v3, vcc
	v_add_co_u32_e32 v8, vcc, s15, v4
	s_mov_b32 s15, 0x16830000
	s_nop 0
	v_addc_co_u32_e32 v9, vcc, 0, v5, vcc
	global_load_dwordx4 v[26:29], v[6:7], off
	global_load_dwordx4 v[30:33], v[8:9], off
	v_add_co_u32_e32 v6, vcc, s15, v2
	s_mov_b32 s15, 0x88000
	s_nop 0
	v_addc_co_u32_e32 v7, vcc, 0, v3, vcc
	v_add_co_u32_e32 v8, vcc, s15, v4
	s_mov_b32 s15, 0x16840000
	s_nop 0
	v_addc_co_u32_e32 v9, vcc, 0, v5, vcc
	v_add_co_u32_e32 v2, vcc, s15, v2
	s_mov_b32 s15, 0xcc000
	s_nop 0
	v_addc_co_u32_e32 v3, vcc, 0, v3, vcc
	v_add_co_u32_e32 v4, vcc, s15, v4
	global_load_dwordx4 v[34:37], v[6:7], off
	global_load_dwordx4 v[38:41], v[8:9], off
	v_addc_co_u32_e32 v5, vcc, 0, v5, vcc
	global_load_dwordx4 v[42:45], v[2:3], off
	global_load_dwordx4 v[46:49], v[4:5], off
	v_ashrrev_i32_e32 v4, 2, v10
	v_and_b32_e32 v4, 0xffffffe0, v4
	v_add_u32_e32 v180, s6, v4
	v_ashrrev_i32_e32 v182, 6, v10
	v_and_b32_e32 v179, 1, v182
	v_mov_b32_e32 v55, v0
	v_lshlrev_b32_e32 v54, 7, v179
	s_waitcnt vmcnt(10)
	v_mul_f32_e32 v2, v11, v12
	ds_bpermute_b32 v2, v1, v2
	v_and_b32_e32 v56, 48, v10
	v_mov_b32_e32 v57, v0
	s_waitcnt vmcnt(8)
	v_mul_f32_e32 v3, v13, v14
	ds_bpermute_b32 v3, v1, v3
	s_waitcnt lgkmcnt(1)
	v_fmac_f32_e32 v2, v11, v12
	ds_bpermute_b32 v5, v176, v2
	s_mov_b32 s6, 0x14610000
	s_mov_b64 s[36:37], 0x14610000
	s_waitcnt lgkmcnt(1)
	v_fmac_f32_e32 v3, v13, v14
	ds_bpermute_b32 v6, v176, v3
	s_waitcnt lgkmcnt(1)
	v_add_f32_e32 v4, v2, v5
	v_and_b32_e32 v2, 31, v223
	v_or_b32_e32 v2, v180, v2
	v_bfe_u32 v178, v10, 4, 2
	v_lshlrev_b32_e32 v51, 1, v50
	s_waitcnt lgkmcnt(0)
	v_add_f32_e32 v5, v3, v6
	ds_bpermute_b32 v6, v175, v4
	ds_bpermute_b32 v7, v175, v5
	v_ashrrev_i32_e32 v3, 31, v2
	v_lshlrev_b64 v[2:3], 11, v[2:3]
	v_lshl_add_u64 v[2:3], s[42:43], 0, v[2:3]
	s_waitcnt lgkmcnt(1)
	v_add_f32_e32 v4, v4, v6
	s_waitcnt lgkmcnt(0)
	v_add_f32_e32 v5, v5, v7
	ds_bpermute_b32 v6, v174, v4
	ds_bpermute_b32 v7, v174, v5
	v_lshl_add_u64 v[2:3], v[2:3], 0, s[30:31]
	v_lshl_add_u64 v[2:3], v[2:3], 0, v[54:55]
	v_lshrrev_b32_e32 v55, 1, v50
	s_waitcnt lgkmcnt(1)
	v_add_f32_e32 v132, v4, v6
	s_waitcnt lgkmcnt(0)
	v_add_f32_e32 v133, v5, v7
	v_and_b32_e32 v56, 32, v232
	v_lshrrev_b32_e32 v56, 1, v56
	v_lshl_add_u64 v[6:7], v[2:3], 0, v[56:57]
	v_add_co_u32_e32 v4, vcc, s6, v6
	s_mov_b32 s6, 0x14610020
	s_nop 0
	v_addc_co_u32_e32 v5, vcc, 0, v7, vcc
	v_lshl_add_u64 v[2:3], v[6:7], 0, s[36:37]
	v_add_co_u32_e32 v6, vcc, s6, v6
	global_load_dwordx4 v[10:13], v[4:5], off
	s_nop 0
	global_load_dwordx4 v[2:5], v[2:3], off offset:64
	v_addc_co_u32_e32 v7, vcc, 0, v7, vcc
	global_load_dwordx4 v[14:17], v[6:7], off
	s_nop 0
	global_load_dwordx4 v[6:9], v[6:7], off offset:64
	v_and_b32_e32 v51, 8, v51
	v_and_b32_e32 v55, 4, v55
	v_and_b32_e32 v57, 0xffffff3, v50
	v_or3_b32 v51, v57, v51, v55
	s_movk_i32 s6, 0x110
	v_mul_lo_u32 v55, v50, s6
	v_mad_u64_u32 v[126:127], s[36:37], v51, s6, v[124:125]
	s_mov_b32 s6, 0x11000
	v_add3_u32 v127, v55, v124, s6
	v_add_u32_e32 v51, 0, v126
	v_add_u32_e32 v55, 0, v127
	s_waitcnt vmcnt(11)
	ds_write_b128 v51, v[18:21]
	s_waitcnt vmcnt(10)
	ds_write_b128 v55, v[22:25]
	s_waitcnt vmcnt(9)
	ds_write_b128 v51, v[26:29] offset:8704
	s_waitcnt vmcnt(8)
	ds_write_b128 v55, v[30:33] offset:8704
	s_waitcnt vmcnt(7)
	ds_write_b128 v51, v[34:37] offset:17408
	s_waitcnt vmcnt(6)
	ds_write_b128 v55, v[38:41] offset:17408
	s_waitcnt vmcnt(5)
	ds_write_b128 v51, v[42:45] offset:26112
	s_waitcnt vmcnt(4)
	ds_write_b128 v55, v[46:49] offset:26112
	s_add_i32 s6, 0, 0x11000
	v_mul_u32_u24_e32 v19, 0x110, v177
	v_add3_u32 v183, s6, v56, v19
	s_lshl_b32 s6, s26, 3
	s_and_b32 s6, s6, 0x700
	ds_bpermute_b32 v134, v173, v132
	ds_bpermute_b32 v135, v173, v133
	s_add_u32 s6, s42, s6
	v_add_u32_e32 v18, 0, v54
	s_addc_u32 s18, s43, 0
	v_add3_u32 v137, v18, v56, v19
	s_add_u32 s26, s6, s47
	v_mov_b64_e32 v[18:19], s[10:11]
	s_addc_u32 s27, s18, s46
	v_mad_i64_i32 v[130:131], s[10:11], v50, s35, v[18:19]
	v_mov_b32_e32 v18, 0
	s_mov_b32 s15, 0
	v_lshl_add_u64 v[128:129], s[26:27], 0, v[52:53]
	v_mov_b32_e32 v19, v18
	v_mov_b32_e32 v20, v18
	v_mov_b32_e32 v21, v18
	v_mov_b32_e32 v22, v18
	v_mov_b32_e32 v23, v18
	v_mov_b32_e32 v24, v18
	v_mov_b32_e32 v25, v18
	v_mov_b32_e32 v26, v18
	v_mov_b32_e32 v27, v18
	v_mov_b32_e32 v28, v18
	v_mov_b32_e32 v29, v18
	v_mov_b32_e32 v30, v18
	v_mov_b32_e32 v31, v18
	v_mov_b32_e32 v32, v18
	v_mov_b32_e32 v33, v18
	v_mov_b32_e32 v38, v18
	v_mov_b32_e32 v39, v18
	v_mov_b32_e32 v40, v18
	v_mov_b32_e32 v41, v18
	v_mov_b32_e32 v46, v18
	v_mov_b32_e32 v47, v18
	v_mov_b32_e32 v48, v18
	v_mov_b32_e32 v49, v18
	v_mov_b32_e32 v62, v18
	v_mov_b32_e32 v63, v18
	v_mov_b32_e32 v64, v18
	v_mov_b32_e32 v65, v18
	v_mov_b32_e32 v74, v18
	v_mov_b32_e32 v75, v18
	v_mov_b32_e32 v76, v18
	v_mov_b32_e32 v77, v18
	v_mov_b32_e32 v34, v18
	v_mov_b32_e32 v35, v18
	v_mov_b32_e32 v36, v18
	v_mov_b32_e32 v37, v18
	v_mov_b32_e32 v42, v18
	v_mov_b32_e32 v43, v18
	v_mov_b32_e32 v44, v18
	v_mov_b32_e32 v45, v18
	v_mov_b32_e32 v50, v18
	v_mov_b32_e32 v51, v18
	v_mov_b32_e32 v52, v18
	v_mov_b32_e32 v53, v18
	v_mov_b32_e32 v54, v18
	v_mov_b32_e32 v55, v18
	v_mov_b32_e32 v56, v18
	v_mov_b32_e32 v57, v18
	v_mov_b32_e32 v58, v18
	v_mov_b32_e32 v59, v18
	v_mov_b32_e32 v60, v18
	v_mov_b32_e32 v61, v18
	v_mov_b32_e32 v66, v18
	v_mov_b32_e32 v67, v18
	v_mov_b32_e32 v68, v18
	v_mov_b32_e32 v69, v18
	v_mov_b32_e32 v70, v18
	v_mov_b32_e32 v71, v18
	v_mov_b32_e32 v72, v18
	v_mov_b32_e32 v73, v18
	v_mov_b32_e32 v78, v18
	v_mov_b32_e32 v79, v18
	v_mov_b32_e32 v80, v18
	v_mov_b32_e32 v81, v18
	v_mov_b32_e32 v122, v18
	v_mov_b32_e32 v123, v18
	s_mov_b32 s11, 0xe054000
	s_mov_b32 s18, 0x16870000
	s_mov_b32 s26, 0xe098000
	s_mov_b32 s27, 0x16880000
	s_mov_b32 s30, 0xe0dc000
	s_mov_b64 s[36:37], 0x40000
	s_waitcnt lgkmcnt(0)
	s_barrier
	s_waitcnt vmcnt(0) lgkmcnt(0)
	v_writelane_b32 v175, s64, 0
	v_writelane_b32 v175, s65, 1
	v_writelane_b32 v175, s66, 2
	v_writelane_b32 v175, s67, 3
	v_writelane_b32 v175, s68, 4
	v_writelane_b32 v175, s69, 5
	v_writelane_b32 v175, s70, 6
	v_writelane_b32 v175, s71, 7
	v_writelane_b32 v175, s72, 8
	v_writelane_b32 v175, s73, 9
	v_writelane_b32 v175, s74, 10
	v_writelane_b32 v175, s75, 11
	v_writelane_b32 v175, s76, 12
	v_writelane_b32 v175, s77, 13
	v_writelane_b32 v175, s78, 14
	v_writelane_b32 v175, s79, 15
	v_lshl_add_u64 v[138:139], v[128:129], 0, v[124:125]
	v_lshl_add_u64 v[140:141], v[130:131], 0, v[124:125]
	s_nop 1
	v_readfirstlane_b32 s64, v138
	v_readfirstlane_b32 s65, v139
	v_readfirstlane_b32 s72, v140
	v_readfirstlane_b32 s73, v141
	s_nop 3
	v_subrev_u32_e32 v124, s64, v138
	v_subrev_u32_e32 v125, s72, v140
	s_add_u32 s66, s64, s97
	s_addc_u32 s67, s65, 0
	s_add_u32 s68, s64, s18
	s_addc_u32 s69, s65, 0
	s_add_u32 s70, s64, s27
	s_addc_u32 s71, s65, 0
	s_add_u32 s64, s64, s96
	s_addc_u32 s65, s65, 0
	s_add_u32 s74, s72, s11
	s_addc_u32 s75, s73, 0
	s_add_u32 s74, s74, 0x100
	s_addc_u32 s75, s75, 0
	s_add_u32 s76, s72, s26
	s_addc_u32 s77, s73, 0
	s_add_u32 s76, s76, 0x100
	s_addc_u32 s77, s77, 0
	s_add_u32 s78, s72, s30
	s_addc_u32 s79, s73, 0
	s_add_u32 s78, s78, 0x100
	s_addc_u32 s79, s79, 0
	s_add_u32 s72, s72, s91
	s_addc_u32 s73, s73, 0
	s_add_u32 s72, s72, 0x100
	s_addc_u32 s73, s73, 0
	v_and_b32_e32 v137, 31, v223
	v_mul_u32_u24_e32 v137, 0x110, v137
	v_lshrrev_b32_e32 v183, 5, v223
	v_lshl_add_u32 v137, v183, 4, v137
	v_add_u32_e32 v183, 0x11000, v137
	v_lshl_add_u32 v137, v179, 7, v137
	s_mov_b32 s15, 0
	s_nop 4
	.p2align 6
.Lattn_nf_loop:
	s_and_b32 s10, s15, 1
	s_mul_i32 s6, s10, 0x8800
	v_add_u32_e32 v136, s6, v137
	v_add_u32_e32 v170, s6, v183
	s_sub_u32 s10, 0x8800, s6
	ds_read_b128 v[98:101], v136 offset:0
	ds_read_b128 v[102:105], v136 offset:32
	ds_read_b128 v[106:109], v136 offset:64
	ds_read_b128 v[110:113], v136 offset:96
	v_add_u32_e32 v171, s10, v126
	v_add_u32_e32 v173, s10, v127
	global_load_dwordx4 v[82:85], v124, s[64:65]
	global_load_dwordx4 v[86:89], v124, s[66:67]
	global_load_dwordx4 v[90:93], v124, s[68:69]
	global_load_dwordx4 v[94:97], v124, s[70:71]
	v_add_u32_e32 v124, s36, v124
	s_waitcnt lgkmcnt(3)
	v_mfma_f32_32x32x16_bf16 v[138:153], v[98:101], v[10:13], 0
	ds_read_b128 v[98:101], v136 offset:8704
	s_waitcnt lgkmcnt(3)
	v_mfma_f32_32x32x16_bf16 v[138:153], v[102:105], v[14:17], v[138:153]
	ds_read_b128 v[102:105], v136 offset:8736
	s_waitcnt lgkmcnt(3)
	v_mfma_f32_32x32x16_bf16 v[138:153], v[106:109], v[2:5], v[138:153]
	ds_read_b128 v[106:109], v136 offset:8768
	s_waitcnt lgkmcnt(3)
	v_mfma_f32_32x32x16_bf16 v[138:153], v[110:113], v[6:9], v[138:153]
	ds_read_b128 v[110:113], v136 offset:8800
	s_waitcnt lgkmcnt(3)
	v_mfma_f32_32x32x16_bf16 v[154:169], v[98:101], v[10:13], 0
	ds_read_b128 v[98:101], v136 offset:17408
	s_nop 7
	v_exp_f32_e32 v138, v138
	v_exp_f32_e32 v139, v139
	v_exp_f32_e32 v140, v140
	v_exp_f32_e32 v141, v141
	v_exp_f32_e32 v142, v142
	v_exp_f32_e32 v143, v143
	v_exp_f32_e32 v144, v144
	v_exp_f32_e32 v145, v145
	s_waitcnt lgkmcnt(3)
	v_mfma_f32_32x32x16_bf16 v[154:169], v[102:105], v[14:17], v[154:169]
	ds_read_b128 v[102:105], v136 offset:17440
	v_add_f32_e32 v122, v138, v122
	v_add_f32_e32 v122, v139, v122
	v_add_f32_e32 v122, v140, v122
	v_add_f32_e32 v122, v141, v122
	v_add_f32_e32 v122, v142, v122
	v_add_f32_e32 v122, v143, v122
	v_add_f32_e32 v122, v144, v122
	v_add_f32_e32 v122, v145, v122
	v_cvt_pk_bf16_f32 v114, v138, v139
	v_cvt_pk_bf16_f32 v115, v140, v141
	v_cvt_pk_bf16_f32 v116, v142, v143
	v_cvt_pk_bf16_f32 v117, v144, v145
	s_waitcnt lgkmcnt(3)
	v_mfma_f32_32x32x16_bf16 v[154:169], v[106:109], v[2:5], v[154:169]
	ds_read_b128 v[106:109], v136 offset:17472
	v_exp_f32_e32 v146, v146
	v_exp_f32_e32 v147, v147
	v_exp_f32_e32 v148, v148
	v_exp_f32_e32 v149, v149
	v_exp_f32_e32 v150, v150
	v_exp_f32_e32 v151, v151
	v_exp_f32_e32 v152, v152
	v_exp_f32_e32 v153, v153
	s_waitcnt lgkmcnt(3)
	v_mfma_f32_32x32x16_bf16 v[154:169], v[110:113], v[6:9], v[154:169]
	ds_read_b128 v[110:113], v136 offset:17504
	v_add_f32_e32 v122, v146, v122
	v_add_f32_e32 v122, v147, v122
	v_add_f32_e32 v122, v148, v122
	v_add_f32_e32 v122, v149, v122
	v_add_f32_e32 v122, v150, v122
	v_add_f32_e32 v122, v151, v122
	v_add_f32_e32 v122, v152, v122
	v_add_f32_e32 v122, v153, v122
	v_cvt_pk_bf16_f32 v118, v146, v147
	v_cvt_pk_bf16_f32 v119, v148, v149
	v_cvt_pk_bf16_f32 v120, v150, v151
	v_cvt_pk_bf16_f32 v121, v152, v153
	ds_read_b128 v[128:131], v170 offset:0
	ds_read_b128 v[184:187], v170 offset:8704
	ds_read_b128 v[188:191], v170 offset:17408
	ds_read_b128 v[192:195], v170 offset:26112
	ds_read_b128 v[196:199], v170 offset:32
	s_waitcnt lgkmcnt(8)
	v_mfma_f32_32x32x16_bf16 v[138:153], v[98:101], v[10:13], 0
	ds_read_b128 v[98:101], v136 offset:26112
	v_exp_f32_e32 v154, v154
	v_exp_f32_e32 v155, v155
	v_exp_f32_e32 v156, v156
	s_waitcnt lgkmcnt(8)
	v_mfma_f32_32x32x16_bf16 v[138:153], v[102:105], v[14:17], v[138:153]
	ds_read_b128 v[102:105], v136 offset:26144
	v_exp_f32_e32 v157, v157
	v_exp_f32_e32 v158, v158
	v_exp_f32_e32 v159, v159
	s_waitcnt lgkmcnt(6)
	v_mfma_f32_32x32x16_bf16 v[18:33], v[128:131], v[114:117], v[18:33]
	ds_read_b128 v[128:131], v170 offset:8736
	v_exp_f32_e32 v160, v160
	v_exp_f32_e32 v161, v161
	v_add_f32_e32 v122, v154, v122
	s_waitcnt lgkmcnt(6)
	v_mfma_f32_32x32x16_bf16 v[34:49], v[184:187], v[114:117], v[34:49]
	ds_read_b128 v[184:187], v170 offset:17440
	v_add_f32_e32 v122, v155, v122
	v_add_f32_e32 v122, v156, v122
	v_add_f32_e32 v122, v157, v122
	s_waitcnt lgkmcnt(6)
	v_mfma_f32_32x32x16_bf16 v[50:65], v[188:191], v[114:117], v[50:65]
	ds_read_b128 v[188:191], v170 offset:26144
	v_add_f32_e32 v122, v158, v122
	v_add_f32_e32 v122, v159, v122
	s_waitcnt lgkmcnt(6)
	v_mfma_f32_32x32x16_bf16 v[66:81], v[192:195], v[114:117], v[66:81]
	v_add_f32_e32 v122, v160, v122
	v_add_f32_e32 v122, v161, v122
	v_cvt_pk_bf16_f32 v114, v154, v155
	v_cvt_pk_bf16_f32 v115, v156, v157
	v_cvt_pk_bf16_f32 v116, v158, v159
	v_cvt_pk_bf16_f32 v117, v160, v161
	v_mfma_f32_32x32x16_bf16 v[138:153], v[106:109], v[2:5], v[138:153]
	ds_read_b128 v[106:109], v136 offset:26176
	v_exp_f32_e32 v162, v162
	v_exp_f32_e32 v163, v163
	v_exp_f32_e32 v164, v164
	v_mfma_f32_32x32x16_bf16 v[138:153], v[110:113], v[6:9], v[138:153]
	ds_read_b128 v[110:113], v136 offset:26208
	v_exp_f32_e32 v165, v165
	v_exp_f32_e32 v166, v166
	v_exp_f32_e32 v167, v167
	s_waitcnt lgkmcnt(7)
	v_mfma_f32_32x32x16_bf16 v[18:33], v[196:199], v[118:121], v[18:33]
	v_exp_f32_e32 v168, v168
	v_exp_f32_e32 v169, v169
	v_add_f32_e32 v122, v162, v122
	s_waitcnt lgkmcnt(4)
	v_mfma_f32_32x32x16_bf16 v[34:49], v[128:131], v[118:121], v[34:49]
	v_add_f32_e32 v122, v163, v122
	v_add_f32_e32 v122, v164, v122
	v_add_f32_e32 v122, v165, v122
	s_waitcnt lgkmcnt(3)
	v_mfma_f32_32x32x16_bf16 v[50:65], v[184:187], v[118:121], v[50:65]
	v_add_f32_e32 v122, v166, v122
	v_add_f32_e32 v122, v167, v122
	s_waitcnt lgkmcnt(2)
	v_mfma_f32_32x32x16_bf16 v[66:81], v[188:191], v[118:121], v[66:81]
	v_add_f32_e32 v122, v168, v122
	v_add_f32_e32 v122, v169, v122
	v_cvt_pk_bf16_f32 v118, v162, v163
	v_cvt_pk_bf16_f32 v119, v164, v165
	v_cvt_pk_bf16_f32 v120, v166, v167
	v_cvt_pk_bf16_f32 v121, v168, v169
	ds_read_b128 v[128:131], v170 offset:64
	ds_read_b128 v[184:187], v170 offset:8768
	ds_read_b128 v[188:191], v170 offset:17472
	ds_read_b128 v[192:195], v170 offset:26176
	ds_read_b128 v[196:199], v170 offset:96
	v_mfma_f32_32x32x16_bf16 v[154:169], v[98:101], v[10:13], 0
	v_exp_f32_e32 v138, v138
	v_exp_f32_e32 v139, v139
	v_exp_f32_e32 v140, v140
	v_mfma_f32_32x32x16_bf16 v[154:169], v[102:105], v[14:17], v[154:169]
	v_exp_f32_e32 v141, v141
	v_exp_f32_e32 v142, v142
	v_exp_f32_e32 v143, v143
	s_waitcnt lgkmcnt(4)
	v_mfma_f32_32x32x16_bf16 v[18:33], v[128:131], v[114:117], v[18:33]
	ds_read_b128 v[128:131], v170 offset:8800
	v_exp_f32_e32 v144, v144
	v_exp_f32_e32 v145, v145
	s_waitcnt vmcnt(3)
	ds_write_b128 v171, v[82:85] offset:0
	s_waitcnt vmcnt(2)
	ds_write_b128 v171, v[86:89] offset:8704
	s_waitcnt vmcnt(1)
	ds_write_b128 v171, v[90:93] offset:17408
	s_waitcnt vmcnt(0)
	ds_write_b128 v171, v[94:97] offset:26112
	v_add_f32_e32 v122, v138, v122
	v_add_f32_e32 v122, v139, v122
	s_waitcnt lgkmcnt(8)
	v_mfma_f32_32x32x16_bf16 v[34:49], v[184:187], v[114:117], v[34:49]
	ds_read_b128 v[184:187], v170 offset:17504
	v_add_f32_e32 v122, v140, v122
	v_add_f32_e32 v122, v141, v122
	s_waitcnt lgkmcnt(8)
	v_mfma_f32_32x32x16_bf16 v[50:65], v[188:191], v[114:117], v[50:65]
	ds_read_b128 v[188:191], v170 offset:26208
	v_add_f32_e32 v122, v142, v122
	v_add_f32_e32 v122, v143, v122
	s_waitcnt lgkmcnt(8)
	v_mfma_f32_32x32x16_bf16 v[66:81], v[192:195], v[114:117], v[66:81]
	v_add_f32_e32 v122, v144, v122
	v_add_f32_e32 v122, v145, v122
	v_cvt_pk_bf16_f32 v114, v138, v139
	v_cvt_pk_bf16_f32 v115, v140, v141
	v_cvt_pk_bf16_f32 v116, v142, v143
	v_cvt_pk_bf16_f32 v117, v144, v145
	v_mfma_f32_32x32x16_bf16 v[154:169], v[106:109], v[2:5], v[154:169]
	v_exp_f32_e32 v146, v146
	v_exp_f32_e32 v147, v147
	v_exp_f32_e32 v148, v148
	v_mfma_f32_32x32x16_bf16 v[154:169], v[110:113], v[6:9], v[154:169]
	v_exp_f32_e32 v149, v149
	v_exp_f32_e32 v150, v150
	v_exp_f32_e32 v151, v151
	s_waitcnt lgkmcnt(7)
	v_mfma_f32_32x32x16_bf16 v[18:33], v[196:199], v[118:121], v[18:33]
	v_exp_f32_e32 v152, v152
	v_exp_f32_e32 v153, v153
	global_load_dwordx4 v[82:85], v125, s[72:73]
	global_load_dwordx4 v[86:89], v125, s[74:75]
	global_load_dwordx4 v[90:93], v125, s[76:77]
	global_load_dwordx4 v[94:97], v125, s[78:79]
	v_add_u32_e32 v125, s38, v125
	v_add_f32_e32 v122, v146, v122
	v_add_f32_e32 v122, v147, v122
	s_waitcnt lgkmcnt(6)
	v_mfma_f32_32x32x16_bf16 v[34:49], v[128:131], v[118:121], v[34:49]
	v_add_f32_e32 v122, v148, v122
	v_add_f32_e32 v122, v149, v122
	s_waitcnt lgkmcnt(1)
	v_mfma_f32_32x32x16_bf16 v[50:65], v[184:187], v[118:121], v[50:65]
	v_add_f32_e32 v122, v150, v122
	v_add_f32_e32 v122, v151, v122
	s_waitcnt lgkmcnt(0)
	v_mfma_f32_32x32x16_bf16 v[66:81], v[188:191], v[118:121], v[66:81]
	v_add_f32_e32 v122, v152, v122
	v_add_f32_e32 v122, v153, v122
	v_cvt_pk_bf16_f32 v118, v146, v147
	v_cvt_pk_bf16_f32 v119, v148, v149
	v_cvt_pk_bf16_f32 v120, v150, v151
	v_cvt_pk_bf16_f32 v121, v152, v153
	ds_read_b128 v[128:131], v170 offset:128
	ds_read_b128 v[184:187], v170 offset:8832
	ds_read_b128 v[188:191], v170 offset:17536
	ds_read_b128 v[192:195], v170 offset:26240
	ds_read_b128 v[196:199], v170 offset:160
	s_waitcnt lgkmcnt(4)
	v_mfma_f32_32x32x16_bf16 v[18:33], v[128:131], v[114:117], v[18:33]
	ds_read_b128 v[128:131], v170 offset:8864
	v_exp_f32_e32 v154, v154
	v_exp_f32_e32 v155, v155
	v_exp_f32_e32 v156, v156
	v_exp_f32_e32 v157, v157
	s_waitcnt lgkmcnt(4)
	v_mfma_f32_32x32x16_bf16 v[34:49], v[184:187], v[114:117], v[34:49]
	ds_read_b128 v[184:187], v170 offset:17568
	v_exp_f32_e32 v158, v158
	v_exp_f32_e32 v159, v159
	v_exp_f32_e32 v160, v160
	v_exp_f32_e32 v161, v161
	s_waitcnt lgkmcnt(4)
	v_mfma_f32_32x32x16_bf16 v[50:65], v[188:191], v[114:117], v[50:65]
	ds_read_b128 v[188:191], v170 offset:26272
	v_add_f32_e32 v122, v154, v122
	v_add_f32_e32 v122, v155, v122
	v_add_f32_e32 v122, v156, v122
	v_add_f32_e32 v122, v157, v122
	s_waitcnt lgkmcnt(4)
	v_mfma_f32_32x32x16_bf16 v[66:81], v[192:195], v[114:117], v[66:81]
	v_add_f32_e32 v122, v158, v122
	v_add_f32_e32 v122, v159, v122
	v_add_f32_e32 v122, v160, v122
	v_add_f32_e32 v122, v161, v122
	v_cvt_pk_bf16_f32 v114, v154, v155
	v_cvt_pk_bf16_f32 v115, v156, v157
	v_cvt_pk_bf16_f32 v116, v158, v159
	v_cvt_pk_bf16_f32 v117, v160, v161
	s_waitcnt lgkmcnt(3)
	v_mfma_f32_32x32x16_bf16 v[18:33], v[196:199], v[118:121], v[18:33]
	v_exp_f32_e32 v162, v162
	v_exp_f32_e32 v163, v163
	v_exp_f32_e32 v164, v164
	v_exp_f32_e32 v165, v165
	s_waitcnt lgkmcnt(2)
	v_mfma_f32_32x32x16_bf16 v[34:49], v[128:131], v[118:121], v[34:49]
	v_exp_f32_e32 v166, v166
	v_exp_f32_e32 v167, v167
	v_exp_f32_e32 v168, v168
	v_exp_f32_e32 v169, v169
	s_waitcnt lgkmcnt(1)
	v_mfma_f32_32x32x16_bf16 v[50:65], v[184:187], v[118:121], v[50:65]
	v_add_f32_e32 v122, v162, v122
	v_add_f32_e32 v122, v163, v122
	v_add_f32_e32 v122, v164, v122
	v_add_f32_e32 v122, v165, v122
	s_waitcnt lgkmcnt(0)
	v_mfma_f32_32x32x16_bf16 v[66:81], v[188:191], v[118:121], v[66:81]
	v_add_f32_e32 v122, v166, v122
	v_add_f32_e32 v122, v167, v122
	v_add_f32_e32 v122, v168, v122
	v_add_f32_e32 v122, v169, v122
	v_cvt_pk_bf16_f32 v118, v162, v163
	v_cvt_pk_bf16_f32 v119, v164, v165
	v_cvt_pk_bf16_f32 v120, v166, v167
	v_cvt_pk_bf16_f32 v121, v168, v169
	ds_read_b128 v[128:131], v170 offset:192
	ds_read_b128 v[184:187], v170 offset:8896
	ds_read_b128 v[188:191], v170 offset:17600
	ds_read_b128 v[192:195], v170 offset:26304
	ds_read_b128 v[196:199], v170 offset:224
	s_waitcnt lgkmcnt(4)
	v_mfma_f32_32x32x16_bf16 v[18:33], v[128:131], v[114:117], v[18:33]
	ds_read_b128 v[128:131], v170 offset:8928
	s_waitcnt lgkmcnt(4)
	v_mfma_f32_32x32x16_bf16 v[34:49], v[184:187], v[114:117], v[34:49]
	ds_read_b128 v[184:187], v170 offset:17632
	s_waitcnt lgkmcnt(4)
	v_mfma_f32_32x32x16_bf16 v[50:65], v[188:191], v[114:117], v[50:65]
	ds_read_b128 v[188:191], v170 offset:26336
	s_waitcnt lgkmcnt(4)
	v_mfma_f32_32x32x16_bf16 v[66:81], v[192:195], v[114:117], v[66:81]
	s_waitcnt lgkmcnt(3)
	v_mfma_f32_32x32x16_bf16 v[18:33], v[196:199], v[118:121], v[18:33]
	s_waitcnt lgkmcnt(2)
	v_mfma_f32_32x32x16_bf16 v[34:49], v[128:131], v[118:121], v[34:49]
	s_waitcnt vmcnt(3)
	ds_write_b128 v173, v[82:85] offset:0
	s_waitcnt vmcnt(2)
	ds_write_b128 v173, v[86:89] offset:8704
	s_waitcnt vmcnt(1)
	ds_write_b128 v173, v[90:93] offset:17408
	s_waitcnt vmcnt(0)
	ds_write_b128 v173, v[94:97] offset:26112
	s_waitcnt lgkmcnt(5)
	v_mfma_f32_32x32x16_bf16 v[50:65], v[184:187], v[118:121], v[50:65]
	s_waitcnt lgkmcnt(4)
	v_mfma_f32_32x32x16_bf16 v[66:81], v[188:191], v[118:121], v[66:81]
	s_waitcnt lgkmcnt(0)
	s_barrier
	s_add_i32 s15, s15, 1
	s_cmp_eq_u32 s15, 34
	s_cbranch_scc0 .Lattn_nf_loop
	v_readlane_b32 s64, v175, 0
	v_readlane_b32 s65, v175, 1
	v_readlane_b32 s66, v175, 2
	v_readlane_b32 s67, v175, 3
	v_readlane_b32 s68, v175, 4
	v_readlane_b32 s69, v175, 5
	v_readlane_b32 s70, v175, 6
	v_readlane_b32 s71, v175, 7
	v_readlane_b32 s72, v175, 8
	v_readlane_b32 s73, v175, 9
	v_readlane_b32 s74, v175, 10
	v_readlane_b32 s75, v175, 11
	v_readlane_b32 s76, v175, 12
	v_readlane_b32 s77, v175, 13
	v_readlane_b32 s78, v175, 14
	v_readlane_b32 s79, v175, 15
	s_nop 4
	v_add_f32_e32 v186, v132, v134
	v_add_f32_e32 v184, v133, v135
	ds_bpermute_b32 v187, v172, v186
	ds_bpermute_b32 v185, v172, v184
	s_mov_b32 s10, 0x3fb8aa3b
	s_mov_b32 s11, 0xc2ce8ed0
	s_mov_b32 s6, 0x42b17218
	v_cmp_eq_u32_e64 s[40:41], 0, v179
	s_lshl_b32 s30, s14, 1
	v_lshlrev_b32_e32 v196, 3, v178
	v_mov_b32_e32 v197, 0
	v_lshlrev_b32_e32 v198, 4, v179
	v_or3_b32 v198, v198, v177, v180
	v_ashrrev_i32_e32 v199, 31, v198
	v_lshlrev_b64 v[198:199], 11, v[198:199]
	s_mov_b64 s[100:101], 0x18a10000
	v_lshl_add_u64 v[198:199], s[42:43], 0, v[198:199]
	v_lshl_add_u64 v[198:199], v[198:199], 0, s[30:31]
	v_lshl_add_u64 v[198:199], v[198:199], 0, v[196:197]
	v_lshl_add_u64 v[198:199], v[198:199], 0, s[100:101]
	global_load_dwordx2 v[146:147], v[198:199], off
	global_load_dwordx2 v[148:149], v[198:199], off offset:32
	global_load_dwordx2 v[150:151], v[198:199], off offset:64
	global_load_dwordx2 v[152:153], v[198:199], off offset:96
	global_load_dwordx2 v[188:189], v[198:199], off offset:128
	global_load_dwordx2 v[190:191], v[198:199], off offset:160
	global_load_dwordx2 v[192:193], v[198:199], off offset:192
	global_load_dwordx2 v[194:195], v[198:199], off offset:224
	s_mov_b64 s[100:101], exec
	s_and_b64 exec, exec, s[4:5]
	s_cbranch_execz .Lpop_skip
	v_readlane_b32 s14, v255, 22
	v_readlane_b32 s15, v255, 23
	v_mov_b32_e32 v224, 1
	s_nop 4
	global_atomic_add v224, v0, v224, s[14:15] sc0
.Lpop_skip:
	s_mov_b64 exec, s[100:101]
	v_mov_b32_e32 v235, 1
	s_load_dwordx2 s[100:101], s[44:45], 0x80
	v_readlane_b32 s14, v255, 36
	v_readlane_b32 s15, v255, 37
	s_nop 3
	s_lshl_b64 s[14:15], s[14:15], 2
	s_waitcnt lgkmcnt(0)
	v_xor_b32_e32 v82, 32, v223
	v_lshlrev_b32_e32 v82, 2, v82
	ds_bpermute_b32 v83, v82, v122
	v_add_f32_e32 v84, v186, v187
	v_mul_f32_e32 v85, 0x3fb8aa3b, v84
	v_fma_f32 v86, v84, s10, -v85
	v_rndne_f32_e32 v87, v85
	v_fmac_f32_e32 v86, 0x32a5705f, v84
	v_sub_f32_e32 v85, v85, v87
	v_add_f32_e32 v85, v85, v86
	v_exp_f32_e32 v85, v85
	v_cvt_i32_f32_e32 v86, v87
	v_cmp_ngt_f32_e32 vcc, s11, v84
	s_nop 0
	v_ldexp_f32 v85, v85, v86
	s_nop 1
	v_cndmask_b32_e32 v85, 0, v85, vcc
	v_cmp_nlt_f32_e32 vcc, s6, v84
	s_nop 1
	v_cndmask_b32_e32 v88, v220, v85, vcc
	v_add_f32_e32 v84, v184, v185
	v_mul_f32_e32 v85, 0x3fb8aa3b, v84
	v_fma_f32 v86, v84, s10, -v85
	v_rndne_f32_e32 v87, v85
	v_fmac_f32_e32 v86, 0x32a5705f, v84
	v_sub_f32_e32 v85, v85, v87
	v_add_f32_e32 v85, v85, v86
	v_exp_f32_e32 v85, v85
	v_cvt_i32_f32_e32 v86, v87
	v_cmp_ngt_f32_e32 vcc, s11, v84
	s_nop 0
	v_ldexp_f32 v85, v85, v86
	s_nop 1
	v_cndmask_b32_e32 v85, 0, v85, vcc
	v_cmp_nlt_f32_e32 vcc, s6, v84
	s_nop 1
	v_cndmask_b32_e32 v89, v220, v85, vcc
	v_sub_f32_e32 v88, v88, v89
	v_add_f32_e32 v88, v236, v88
	s_nop 1
	v_cndmask_b32_e64 v88, -v88, 1.0, s[40:41]
	s_waitcnt lgkmcnt(0)
	v_add_f32_e32 v83, v122, v83
	v_div_scale_f32 v90, s[10:11], v83, v83, v88
	v_rcp_f32_e32 v91, v90
	s_nop 0
	v_fma_f32 v92, -v90, v91, 1.0
	v_fmac_f32_e32 v91, v92, v91
	v_div_scale_f32 v92, vcc, v88, v83, v88
	v_mul_f32_e32 v93, v92, v91
	v_fma_f32 v94, -v90, v93, v92
	v_fmac_f32_e32 v93, v94, v91
	v_fma_f32 v90, -v90, v93, v92
	s_nop 1
	v_div_fmas_f32 v90, v90, v91, v93
	v_div_fixup_f32 v96, v90, v83, v88
	v_and_b32_e32 v98, 31, v223
	v_mul_u32_u24_e32 v98, 528, v98
	v_lshrrev_b32_e32 v99, 5, v223
	v_lshl_add_u32 v98, v99, 4, v98
	s_movk_i32 s6, 0x4200
	v_mad_u32_u24 v98, v182, s6, v98
	v_pk_mul_f32 v[18:19], v[18:19], v[96:97] op_sel_hi:[1,0]
	v_pk_mul_f32 v[20:21], v[20:21], v[96:97] op_sel_hi:[1,0]
	v_pk_mul_f32 v[22:23], v[22:23], v[96:97] op_sel_hi:[1,0]
	v_pk_mul_f32 v[24:25], v[24:25], v[96:97] op_sel_hi:[1,0]
	v_pk_mul_f32 v[26:27], v[26:27], v[96:97] op_sel_hi:[1,0]
	v_pk_mul_f32 v[28:29], v[28:29], v[96:97] op_sel_hi:[1,0]
	v_pk_mul_f32 v[30:31], v[30:31], v[96:97] op_sel_hi:[1,0]
	v_pk_mul_f32 v[32:33], v[32:33], v[96:97] op_sel_hi:[1,0]
	ds_write_b128 v98, v[18:21] offset:0
	ds_write_b128 v98, v[22:25] offset:32
	ds_write_b128 v98, v[26:29] offset:64
	ds_write_b128 v98, v[30:33] offset:96
	v_pk_mul_f32 v[34:35], v[34:35], v[96:97] op_sel_hi:[1,0]
	v_pk_mul_f32 v[36:37], v[36:37], v[96:97] op_sel_hi:[1,0]
	v_pk_mul_f32 v[38:39], v[38:39], v[96:97] op_sel_hi:[1,0]
	v_pk_mul_f32 v[40:41], v[40:41], v[96:97] op_sel_hi:[1,0]
	v_pk_mul_f32 v[42:43], v[42:43], v[96:97] op_sel_hi:[1,0]
	v_pk_mul_f32 v[44:45], v[44:45], v[96:97] op_sel_hi:[1,0]
	v_pk_mul_f32 v[46:47], v[46:47], v[96:97] op_sel_hi:[1,0]
	v_pk_mul_f32 v[48:49], v[48:49], v[96:97] op_sel_hi:[1,0]
	ds_write_b128 v98, v[34:37] offset:128
	ds_write_b128 v98, v[38:41] offset:160
	ds_write_b128 v98, v[42:45] offset:192
	ds_write_b128 v98, v[46:49] offset:224
	s_waitcnt lgkmcnt(0)
	v_pk_mul_f32 v[50:51], v[50:51], v[96:97] op_sel_hi:[1,0]
	v_pk_mul_f32 v[52:53], v[52:53], v[96:97] op_sel_hi:[1,0]
	v_pk_mul_f32 v[54:55], v[54:55], v[96:97] op_sel_hi:[1,0]
	v_pk_mul_f32 v[56:57], v[56:57], v[96:97] op_sel_hi:[1,0]
	v_pk_mul_f32 v[58:59], v[58:59], v[96:97] op_sel_hi:[1,0]
	v_pk_mul_f32 v[60:61], v[60:61], v[96:97] op_sel_hi:[1,0]
	v_pk_mul_f32 v[62:63], v[62:63], v[96:97] op_sel_hi:[1,0]
	v_pk_mul_f32 v[64:65], v[64:65], v[96:97] op_sel_hi:[1,0]
	ds_write_b128 v98, v[50:53] offset:256
	ds_write_b128 v98, v[54:57] offset:288
	ds_write_b128 v98, v[58:61] offset:320
	ds_write_b128 v98, v[62:65] offset:352
	v_pk_mul_f32 v[66:67], v[66:67], v[96:97] op_sel_hi:[1,0]
	v_pk_mul_f32 v[68:69], v[68:69], v[96:97] op_sel_hi:[1,0]
	v_pk_mul_f32 v[70:71], v[70:71], v[96:97] op_sel_hi:[1,0]
	v_pk_mul_f32 v[72:73], v[72:73], v[96:97] op_sel_hi:[1,0]
	v_pk_mul_f32 v[74:75], v[74:75], v[96:97] op_sel_hi:[1,0]
	v_pk_mul_f32 v[76:77], v[76:77], v[96:97] op_sel_hi:[1,0]
	v_pk_mul_f32 v[78:79], v[78:79], v[96:97] op_sel_hi:[1,0]
	v_pk_mul_f32 v[80:81], v[80:81], v[96:97] op_sel_hi:[1,0]
	ds_write_b128 v98, v[66:69] offset:384
	ds_write_b128 v98, v[70:73] offset:416
	ds_write_b128 v98, v[74:77] offset:448
	ds_write_b128 v98, v[78:81] offset:480
	s_waitcnt lgkmcnt(0)
	s_barrier
	s_add_u32 s100, s100, s14
	s_addc_u32 s101, s101, s15
	v_lshlrev_b32_e32 v132, 4, v178
	global_load_dwordx4 v[100:103], v132, s[100:101]
	global_load_dwordx4 v[104:107], v132, s[100:101] offset:64
	global_load_dwordx4 v[108:111], v132, s[100:101] offset:128
	global_load_dwordx4 v[112:115], v132, s[100:101] offset:192
	global_load_dwordx4 v[116:119], v132, s[100:101] offset:256
	global_load_dwordx4 v[120:123], v132, s[100:101] offset:320
	global_load_dwordx4 v[124:127], v132, s[100:101] offset:384
	global_load_dwordx4 v[128:131], v132, s[100:101] offset:448
	v_lshl_add_u32 v99, v179, 4, v177
	v_mul_u32_u24_e32 v99, 528, v99
	v_lshl_add_u32 v99, v178, 4, v99
	v_mad_u32_u24 v154, v182, s6, v99
	v_xor_b32_e32 v155, 1, v182
	v_mad_u32_u24 v155, v155, s6, v99
	ds_read_b128 v[82:85], v154 offset:0
	ds_read_b128 v[156:159], v155 offset:0
	ds_read_b128 v[86:89], v154 offset:64
	ds_read_b128 v[160:163], v155 offset:64
	ds_read_b128 v[90:93], v154 offset:128
	ds_read_b128 v[164:167], v155 offset:128
	ds_read_b128 v[94:97], v154 offset:192
	ds_read_b128 v[168:171], v155 offset:192
	s_waitcnt lgkmcnt(6)
	v_add_f32_e32 v38, v82, v156
	v_add_f32_e32 v39, v83, v157
	v_add_f32_e32 v36, v84, v158
	v_add_f32_e32 v37, v85, v159
	v_mul_f32_e32 v2, v38, v38
	v_fmac_f32_e32 v2, v39, v39
	v_fmac_f32_e32 v2, v36, v36
	v_fmac_f32_e32 v2, v37, v37
	s_waitcnt lgkmcnt(4)
	v_add_f32_e32 v34, v86, v160
	v_add_f32_e32 v35, v87, v161
	v_add_f32_e32 v32, v88, v162
	v_add_f32_e32 v33, v89, v163
	v_fmac_f32_e32 v2, v34, v34
	v_fmac_f32_e32 v2, v35, v35
	v_fmac_f32_e32 v2, v32, v32
	v_fmac_f32_e32 v2, v33, v33
	s_waitcnt lgkmcnt(2)
	v_add_f32_e32 v30, v90, v164
	v_add_f32_e32 v31, v91, v165
	v_add_f32_e32 v28, v92, v166
	v_add_f32_e32 v29, v93, v167
	v_fmac_f32_e32 v2, v30, v30
	v_fmac_f32_e32 v2, v31, v31
	v_fmac_f32_e32 v2, v28, v28
	v_fmac_f32_e32 v2, v29, v29
	s_waitcnt lgkmcnt(0)
	v_add_f32_e32 v26, v94, v168
	v_add_f32_e32 v27, v95, v169
	v_add_f32_e32 v24, v96, v170
	v_add_f32_e32 v25, v97, v171
	v_fmac_f32_e32 v2, v26, v26
	v_fmac_f32_e32 v2, v27, v27
	v_fmac_f32_e32 v2, v24, v24
	v_fmac_f32_e32 v2, v25, v25
	ds_read_b128 v[82:85], v154 offset:256
	ds_read_b128 v[156:159], v155 offset:256
	ds_read_b128 v[86:89], v154 offset:320
	ds_read_b128 v[160:163], v155 offset:320
	ds_read_b128 v[90:93], v154 offset:384
	ds_read_b128 v[164:167], v155 offset:384
	ds_read_b128 v[94:97], v154 offset:448
	ds_read_b128 v[168:171], v155 offset:448
	s_waitcnt lgkmcnt(6)
	v_add_f32_e32 v22, v82, v156
	v_add_f32_e32 v23, v83, v157
	v_add_f32_e32 v20, v84, v158
	v_add_f32_e32 v21, v85, v159
	v_fmac_f32_e32 v2, v22, v22
	v_fmac_f32_e32 v2, v23, v23
	v_fmac_f32_e32 v2, v20, v20
	v_fmac_f32_e32 v2, v21, v21
	s_waitcnt lgkmcnt(4)
	v_add_f32_e32 v18, v86, v160
	v_add_f32_e32 v19, v87, v161
	v_add_f32_e32 v16, v88, v162
	v_add_f32_e32 v17, v89, v163
	v_fmac_f32_e32 v2, v18, v18
	v_fmac_f32_e32 v2, v19, v19
	v_fmac_f32_e32 v2, v16, v16
	v_fmac_f32_e32 v2, v17, v17
	s_waitcnt lgkmcnt(2)
	v_add_f32_e32 v14, v90, v164
	v_add_f32_e32 v15, v91, v165
	v_add_f32_e32 v12, v92, v166
	v_add_f32_e32 v13, v93, v167
	v_fmac_f32_e32 v2, v14, v14
	v_fmac_f32_e32 v2, v15, v15
	v_fmac_f32_e32 v2, v12, v12
	v_fmac_f32_e32 v2, v13, v13
	s_waitcnt lgkmcnt(0)
	v_add_f32_e32 v8, v94, v168
	v_add_f32_e32 v9, v95, v169
	v_add_f32_e32 v6, v96, v170
	v_add_f32_e32 v7, v97, v171
	v_fmac_f32_e32 v2, v8, v8
	v_fmac_f32_e32 v2, v9, v9
	v_fmac_f32_e32 v2, v6, v6
	v_fmac_f32_e32 v2, v7, v7
	ds_bpermute_b32 v3, v176, v2
	s_load_dwordx2 s[10:11], s[44:45], 0x80
	v_lshlrev_b32_e32 v4, 3, v178
	v_mov_b32_e32 v5, v0
	s_mov_b32 s6, 0x18a10000
	s_waitcnt lgkmcnt(0)
	v_add_f32_e32 v2, v2, v3
	ds_bpermute_b32 v1, v1, v2
	s_add_u32 s10, s10, s14
	s_addc_u32 s11, s11, s15
	s_mov_b64 s[14:15], 0x18a10000
	v_lshlrev_b32_e32 v44, 4, v178
	s_waitcnt lgkmcnt(0)
	v_add_f32_e32 v1, v2, v1
	v_fmamk_f32 v1, v1, 0x3c000000, v234
	v_cmp_gt_f32_e32 vcc, s90, v1
	v_mul_f32_e32 v2, 0x4b800000, v1
	s_nop 0
	v_cndmask_b32_e32 v1, v1, v2, vcc
	v_rsq_f32_e32 v1, v1
	s_nop 0
	v_mul_f32_e32 v2, 0x45800000, v1
	v_cndmask_b32_e32 v1, v1, v2, vcc
	v_lshlrev_b32_e32 v2, 4, v179
	v_or3_b32 v2, v2, v177, v180
	v_ashrrev_i32_e32 v3, 31, v2
	v_lshlrev_b64 v[2:3], 11, v[2:3]
	v_lshl_add_u64 v[2:3], s[42:43], 0, v[2:3]
	v_lshl_add_u64 v[2:3], v[2:3], 0, s[30:31]
	v_lshl_add_u64 v[2:3], v[2:3], 0, v[4:5]
	v_add_co_u32_e32 v40, vcc, s6, v2
	v_lshl_add_u64 v[10:11], v[2:3], 0, s[14:15]
	s_nop 0
	v_addc_co_u32_e32 v41, vcc, 0, v3, vcc
	v_mul_f32_e32 v1, v227, v1
	v_mul_f32_e32 v38, v38, v1
	v_mul_f32_e32 v36, v36, v1
	v_mul_f32_e32 v34, v34, v1
	v_mul_f32_e32 v32, v32, v1
	v_mul_f32_e32 v30, v30, v1
	v_mul_f32_e32 v28, v28, v1
	v_mul_f32_e32 v26, v26, v1
	v_mul_f32_e32 v24, v24, v1
	v_mul_f32_e32 v22, v22, v1
	v_mul_f32_e32 v20, v20, v1
	v_mul_f32_e32 v18, v18, v1
	v_mul_f32_e32 v16, v16, v1
	v_mul_f32_e32 v14, v14, v1
	v_mul_f32_e32 v12, v12, v1
	s_waitcnt vmcnt(0)
	v_readfirstlane_b32 s101, v224
	v_mov_b32_e32 v42, v146
	v_mov_b32_e32 v43, v147
	v_mov_b32_e32 v2, v100
	v_mov_b32_e32 v3, v101
	v_mov_b32_e32 v4, v102
	v_mov_b32_e32 v5, v103
	v_mul_f32_e32 v2, v2, v38
	v_lshlrev_b32_e32 v38, 16, v42
	v_mul_f32_e32 v2, v2, v38
	v_mul_f32_e32 v38, v39, v1
	v_mul_f32_e32 v4, v4, v36
	v_lshlrev_b32_e32 v36, 16, v43
	v_mul_f32_e32 v3, v3, v38
	v_and_b32_e32 v38, 0xffff0000, v42
	v_mul_f32_e32 v4, v4, v36
	v_mul_f32_e32 v36, v37, v1
	v_mul_f32_e32 v3, v3, v38
	v_mul_f32_e32 v5, v5, v36
	v_and_b32_e32 v36, 0xffff0000, v43
	v_mul_f32_e32 v5, v5, v36
	s_nop 1
	v_cvt_pk_bf16_f32 v2, v2, v3
	s_nop 1
	v_cvt_pk_bf16_f32 v3, v4, v5
	global_store_dwordx2 v[40:41], v[2:3], off
	v_mov_b32_e32 v36, v148
	v_mov_b32_e32 v37, v149
	s_nop 0
	v_mov_b32_e32 v2, v104
	v_mov_b32_e32 v3, v105
	v_mov_b32_e32 v4, v106
	v_mov_b32_e32 v5, v107
	v_mul_f32_e32 v2, v2, v34
	v_lshlrev_b32_e32 v34, 16, v36
	v_mul_f32_e32 v2, v2, v34
	v_mul_f32_e32 v34, v35, v1
	v_mul_f32_e32 v4, v4, v32
	v_lshlrev_b32_e32 v32, 16, v37
	v_mul_f32_e32 v3, v3, v34
	v_and_b32_e32 v34, 0xffff0000, v36
	v_mul_f32_e32 v4, v4, v32
	v_mul_f32_e32 v32, v33, v1
	v_mul_f32_e32 v3, v3, v34
	v_mul_f32_e32 v5, v5, v32
	v_and_b32_e32 v32, 0xffff0000, v37
	v_mul_f32_e32 v5, v5, v32
	s_nop 1
	v_cvt_pk_bf16_f32 v2, v2, v3
	s_nop 1
	v_cvt_pk_bf16_f32 v3, v4, v5
	global_store_dwordx2 v[10:11], v[2:3], off offset:32
	v_mov_b32_e32 v32, v150
	v_mov_b32_e32 v33, v151
	s_nop 0
	v_mov_b32_e32 v2, v108
	v_mov_b32_e32 v3, v109
	v_mov_b32_e32 v4, v110
	v_mov_b32_e32 v5, v111
	v_mul_f32_e32 v2, v2, v30
	v_lshlrev_b32_e32 v30, 16, v32
	v_mul_f32_e32 v2, v2, v30
	v_mul_f32_e32 v30, v31, v1
	v_mul_f32_e32 v4, v4, v28
	v_lshlrev_b32_e32 v28, 16, v33
	v_mul_f32_e32 v3, v3, v30
	v_and_b32_e32 v30, 0xffff0000, v32
	v_mul_f32_e32 v4, v4, v28
	v_mul_f32_e32 v28, v29, v1
	v_mul_f32_e32 v3, v3, v30
	v_mul_f32_e32 v5, v5, v28
	v_and_b32_e32 v28, 0xffff0000, v33
	v_mul_f32_e32 v5, v5, v28
	s_nop 1
	v_cvt_pk_bf16_f32 v2, v2, v3
	s_nop 1
	v_cvt_pk_bf16_f32 v3, v4, v5
	global_store_dwordx2 v[10:11], v[2:3], off offset:64
	v_mov_b32_e32 v28, v152
	v_mov_b32_e32 v29, v153
	s_nop 0
	v_mov_b32_e32 v2, v112
	v_mov_b32_e32 v3, v113
	v_mov_b32_e32 v4, v114
	v_mov_b32_e32 v5, v115
	v_mul_f32_e32 v2, v2, v26
	v_lshlrev_b32_e32 v26, 16, v28
	v_mul_f32_e32 v2, v2, v26
	v_mul_f32_e32 v26, v27, v1
	v_mul_f32_e32 v4, v4, v24
	v_lshlrev_b32_e32 v24, 16, v29
	v_mul_f32_e32 v3, v3, v26
	v_and_b32_e32 v26, 0xffff0000, v28
	v_mul_f32_e32 v4, v4, v24
	v_mul_f32_e32 v24, v25, v1
	v_mul_f32_e32 v3, v3, v26
	v_mul_f32_e32 v5, v5, v24
	v_and_b32_e32 v24, 0xffff0000, v29
	v_mul_f32_e32 v5, v5, v24
	s_nop 1
	v_cvt_pk_bf16_f32 v2, v2, v3
	s_nop 1
	v_cvt_pk_bf16_f32 v3, v4, v5
	global_store_dwordx2 v[10:11], v[2:3], off offset:96
	v_mov_b32_e32 v24, v188
	v_mov_b32_e32 v25, v189
	s_nop 0
	v_mov_b32_e32 v2, v116
	v_mov_b32_e32 v3, v117
	v_mov_b32_e32 v4, v118
	v_mov_b32_e32 v5, v119
	v_mul_f32_e32 v2, v2, v22
	v_lshlrev_b32_e32 v22, 16, v24
	v_mul_f32_e32 v2, v2, v22
	v_mul_f32_e32 v22, v23, v1
	v_mul_f32_e32 v4, v4, v20
	v_lshlrev_b32_e32 v20, 16, v25
	v_mul_f32_e32 v3, v3, v22
	v_and_b32_e32 v22, 0xffff0000, v24
	v_mul_f32_e32 v4, v4, v20
	v_mul_f32_e32 v20, v21, v1
	v_mul_f32_e32 v3, v3, v22
	v_mul_f32_e32 v5, v5, v20
	v_and_b32_e32 v20, 0xffff0000, v25
	v_mul_f32_e32 v5, v5, v20
	s_nop 1
	v_cvt_pk_bf16_f32 v2, v2, v3
	s_nop 1
	v_cvt_pk_bf16_f32 v3, v4, v5
	global_store_dwordx2 v[10:11], v[2:3], off offset:128
	v_mov_b32_e32 v20, v190
	v_mov_b32_e32 v21, v191
	s_nop 0
	v_mov_b32_e32 v2, v120
	v_mov_b32_e32 v3, v121
	v_mov_b32_e32 v4, v122
	v_mov_b32_e32 v5, v123
	v_mul_f32_e32 v2, v2, v18
	v_lshlrev_b32_e32 v18, 16, v20
	v_mul_f32_e32 v2, v2, v18
	v_mul_f32_e32 v18, v19, v1
	v_mul_f32_e32 v4, v4, v16
	v_lshlrev_b32_e32 v16, 16, v21
	v_mul_f32_e32 v3, v3, v18
	v_and_b32_e32 v18, 0xffff0000, v20
	v_mul_f32_e32 v4, v4, v16
	v_mul_f32_e32 v16, v17, v1
	v_mul_f32_e32 v3, v3, v18
	v_mul_f32_e32 v5, v5, v16
	v_and_b32_e32 v16, 0xffff0000, v21
	v_mul_f32_e32 v5, v5, v16
	s_nop 1
	v_cvt_pk_bf16_f32 v2, v2, v3
	s_nop 1
	v_cvt_pk_bf16_f32 v3, v4, v5
	global_store_dwordx2 v[10:11], v[2:3], off offset:160
	v_mov_b32_e32 v16, v192
	v_mov_b32_e32 v17, v193
	s_nop 0
	v_mov_b32_e32 v2, v124
	v_mov_b32_e32 v3, v125
	v_mov_b32_e32 v4, v126
	v_mov_b32_e32 v5, v127
	v_mul_f32_e32 v2, v2, v14
	v_lshlrev_b32_e32 v14, 16, v16
	v_mul_f32_e32 v2, v2, v14
	v_mul_f32_e32 v14, v15, v1
	v_mul_f32_e32 v4, v4, v12
	v_lshlrev_b32_e32 v12, 16, v17
	v_mul_f32_e32 v3, v3, v14
	v_and_b32_e32 v14, 0xffff0000, v16
	v_mul_f32_e32 v4, v4, v12
	v_mul_f32_e32 v12, v13, v1
	v_mul_f32_e32 v3, v3, v14
	v_mul_f32_e32 v5, v5, v12
	v_and_b32_e32 v12, 0xffff0000, v17
	v_mul_f32_e32 v5, v5, v12
	s_nop 1
	v_cvt_pk_bf16_f32 v2, v2, v3
	s_nop 1
	v_cvt_pk_bf16_f32 v3, v4, v5
	global_store_dwordx2 v[10:11], v[2:3], off offset:192
	v_mov_b32_e32 v2, v194
	v_mov_b32_e32 v3, v195
	s_nop 0
	v_mov_b32_e32 v12, v128
	v_mov_b32_e32 v13, v129
	v_mov_b32_e32 v14, v130
	v_mov_b32_e32 v15, v131
	v_mul_f32_e32 v4, v8, v1
	v_lshlrev_b32_e32 v5, 16, v2
	v_mul_f32_e32 v4, v4, v12
	v_mul_f32_e32 v4, v4, v5
	v_mul_f32_e32 v5, v9, v1
	v_mul_f32_e32 v5, v5, v13
	v_and_b32_e32 v2, 0xffff0000, v2
	v_mul_f32_e32 v2, v5, v2
	v_mul_f32_e32 v5, v6, v1
	v_mul_f32_e32 v1, v7, v1
	v_mul_f32_e32 v5, v5, v14
	v_lshlrev_b32_e32 v6, 16, v3
	v_mul_f32_e32 v1, v1, v15
	v_and_b32_e32 v3, 0xffff0000, v3
	v_mul_f32_e32 v5, v5, v6
	v_mul_f32_e32 v1, v1, v3
	s_nop 1
	v_cvt_pk_bf16_f32 v2, v4, v2
	s_nop 1
	v_cvt_pk_bf16_f32 v3, v5, v1
	global_store_dwordx2 v[10:11], v[2:3], off offset:224
	s_barrier
